# grid barrier spin loops poll without s_sleep 1
# baseline (speedup 1.0000x reference)
; __device__ __forceinline__ unsigned xb_ld(unsigned* p)              { return __hip_atomic_load(p, __ATOMIC_RELAXED, __HIP_MEMORY_SCOPE_AGENT); }
; __device__ __forceinline__ void xcd_barrier_complete(unsigned* bar, unsigned x, unsigned& nloc, unsigned& nx) {
;     ...
;     for (;;) {
;         sum = 0u; cnt = 0u; mine = 0u;
; #pragma unroll
;         for (unsigned j = 0; j < 16; ++j) { const unsigned c = xb_ld(&bar[XB_XCNT(j)]); sum += c; cnt += (c > 0u) ? 1u : 0u; mine = (j == x) ? c : mine; }
;         if (sum == G) break;
;         __builtin_amdgcn_s_sleep(1);
;         if ((++sp & 255u) == 0u) { if (xb_ld(&bar[XB_TMO])) break; if (sp > XB_SPIN_CAP) { atomicAdd(&bar[XB_TMO], 1u); break; } }
;     }
.LBB0_105:
	global_load_dword v15, v139, s[84:85] offset:1024 sc1
	global_load_dword v0, v139, s[84:85] offset:1280 sc1
	global_load_dword v1, v139, s[84:85] offset:1536 sc1
	global_load_dword v2, v139, s[84:85] offset:1792 sc1
	global_load_dword v3, v139, s[84:85] offset:2048 sc1
	global_load_dword v4, v139, s[84:85] offset:2304 sc1
	global_load_dword v5, v139, s[84:85] offset:2560 sc1
	global_load_dword v6, v139, s[84:85] offset:2816 sc1
	global_load_dword v7, v139, s[84:85] offset:3072 sc1
	global_load_dword v8, v139, s[84:85] offset:3328 sc1
	global_load_dword v9, v139, s[84:85] offset:3584 sc1
	global_load_dword v10, v139, s[84:85] offset:3840 sc1
	global_load_dword v11, v139, s[14:15] sc1
	global_load_dword v12, v139, s[16:17] sc1
	global_load_dword v13, v139, s[18:19] sc1
	global_load_dword v14, v139, s[20:21] sc1
	s_mov_b64 s[38:39], -1
	s_mov_b64 s[40:41], -1
	s_waitcnt vmcnt(14)
	v_add_u32_e32 v16, v0, v15
	s_waitcnt vmcnt(13)
	v_add_u32_e32 v16, v16, v1
	s_waitcnt vmcnt(12)
	v_add_u32_e32 v16, v16, v2
	s_waitcnt vmcnt(11)
	v_add_u32_e32 v16, v16, v3
	s_waitcnt vmcnt(10)
	v_add_u32_e32 v16, v16, v4
	s_waitcnt vmcnt(9)
	v_add_u32_e32 v16, v16, v5
	s_waitcnt vmcnt(8)
	v_add_u32_e32 v16, v16, v6
	s_waitcnt vmcnt(7)
	v_add_u32_e32 v16, v16, v7
	s_waitcnt vmcnt(6)
	v_add_u32_e32 v16, v16, v8
	s_waitcnt vmcnt(5)
	v_add_u32_e32 v16, v16, v9
	s_waitcnt vmcnt(4)
	v_add_u32_e32 v16, v16, v10
	s_waitcnt vmcnt(3)
	v_add_u32_e32 v16, v16, v11
	s_waitcnt vmcnt(2)
	v_add_u32_e32 v16, v16, v12
	s_waitcnt vmcnt(1)
	v_add_u32_e32 v16, v16, v13
	s_waitcnt vmcnt(0)
	v_add_u32_e32 v16, v16, v14
	v_cmp_eq_u32_e32 vcc, s0, v16
	s_cbranch_vccnz .LBB0_104
	s_and_b32 s6, s1, 0xff
	s_cmp_eq_u32 s6, 0
	s_mov_b64 s[42:43], -1
	s_cbranch_scc1 .LBB0_109
	s_and_b64 vcc, exec, s[42:43]
	s_cbranch_vccz .LBB0_104

.LBB0_123:
	s_and_b32 s1, s0, 0xff
	s_mov_b64 s[46:47], -1
	s_cmp_lg_u32 s1, 0
	s_mov_b64 s[50:51], -1
	s_cbranch_scc0 .LBB0_126
	s_and_b64 vcc, exec, s[50:51]
	s_cbranch_vccz .LBB0_122

.LBB0_699:
	s_and_b32 s1, s0, 0xff
	s_mov_b64 s[48:49], -1
	s_cmp_lg_u32 s1, 0
	s_mov_b64 s[52:53], -1
	s_cbranch_scc0 .LBB0_702
	s_and_b64 vcc, exec, s[52:53]
	s_cbranch_vccz .LBB0_698

; __device__ __forceinline__ unsigned xb_ld(unsigned* p)              { return __hip_atomic_load(p, __ATOMIC_RELAXED, __HIP_MEMORY_SCOPE_AGENT); }
; __device__ __forceinline__ void xcd_barrier_complete(unsigned* bar, unsigned x, unsigned& nloc, unsigned& nx) {
;     ...
;     for (;;) {
;         sum = 0u; cnt = 0u; mine = 0u;
; #pragma unroll
;         for (unsigned j = 0; j < 16; ++j) { const unsigned c = xb_ld(&bar[XB_XCNT(j)]); sum += c; cnt += (c > 0u) ? 1u : 0u; mine = (j == x) ? c : mine; }
;         if (sum == G) break;
;         __builtin_amdgcn_s_sleep(1);
;         if ((++sp & 255u) == 0u) { if (xb_ld(&bar[XB_TMO])) break; if (sp > XB_SPIN_CAP) { atomicAdd(&bar[XB_TMO], 1u); break; } }
;     }
.LBB0_751:
	global_load_dword v15, v139, s[84:85] offset:1024 sc1
	global_load_dword v0, v139, s[84:85] offset:1280 sc1
	global_load_dword v1, v139, s[84:85] offset:1536 sc1
	global_load_dword v2, v139, s[84:85] offset:1792 sc1
	global_load_dword v3, v139, s[84:85] offset:2048 sc1
	global_load_dword v4, v139, s[84:85] offset:2304 sc1
	global_load_dword v5, v139, s[84:85] offset:2560 sc1
	global_load_dword v6, v139, s[84:85] offset:2816 sc1
	global_load_dword v7, v139, s[84:85] offset:3072 sc1
	global_load_dword v8, v139, s[84:85] offset:3328 sc1
	global_load_dword v9, v139, s[84:85] offset:3584 sc1
	global_load_dword v10, v139, s[84:85] offset:3840 sc1
	global_load_dword v11, v139, s[14:15] sc1
	global_load_dword v12, v139, s[16:17] sc1
	global_load_dword v13, v139, s[18:19] sc1
	global_load_dword v14, v139, s[20:21] sc1
	s_mov_b64 s[28:29], -1
	s_mov_b64 s[38:39], -1
	s_waitcnt vmcnt(14)
	v_add_u32_e32 v16, v0, v15
	s_waitcnt vmcnt(13)
	v_add_u32_e32 v16, v16, v1
	s_waitcnt vmcnt(12)
	v_add_u32_e32 v16, v16, v2
	s_waitcnt vmcnt(11)
	v_add_u32_e32 v16, v16, v3
	s_waitcnt vmcnt(10)
	v_add_u32_e32 v16, v16, v4
	s_waitcnt vmcnt(9)
	v_add_u32_e32 v16, v16, v5
	s_waitcnt vmcnt(8)
	v_add_u32_e32 v16, v16, v6
	s_waitcnt vmcnt(7)
	v_add_u32_e32 v16, v16, v7
	s_waitcnt vmcnt(6)
	v_add_u32_e32 v16, v16, v8
	s_waitcnt vmcnt(5)
	v_add_u32_e32 v16, v16, v9
	s_waitcnt vmcnt(4)
	v_add_u32_e32 v16, v16, v10
	s_waitcnt vmcnt(3)
	v_add_u32_e32 v16, v16, v11
	s_waitcnt vmcnt(2)
	v_add_u32_e32 v16, v16, v12
	s_waitcnt vmcnt(1)
	v_add_u32_e32 v16, v16, v13
	s_waitcnt vmcnt(0)
	v_add_u32_e32 v16, v16, v14
	v_cmp_eq_u32_e32 vcc, s0, v16
	s_cbranch_vccnz .LBB0_750
	s_and_b32 s6, s1, 0xff
	s_cmp_eq_u32 s6, 0
	s_mov_b64 s[40:41], -1
	s_cbranch_scc1 .LBB0_755
	s_and_b64 vcc, exec, s[40:41]
	s_cbranch_vccz .LBB0_750

.LBB0_769:
	s_and_b32 s1, s0, 0xff
	s_mov_b64 s[44:45], -1
	s_cmp_lg_u32 s1, 0
	s_mov_b64 s[48:49], -1
	s_cbranch_scc0 .LBB0_772
	s_and_b64 vcc, exec, s[48:49]
	s_cbranch_vccz .LBB0_768
